# E38: attention prologue issues tile-1 K/V loads together with tile-0 loads (one less exposed memory latency per half-unit)
# speedup vs baseline: 1.0011x; 1.0011x over previous
.LBB0_2190:
	s_add_u32 s8, s50, s6
	s_addc_u32 s13, s51, s7
	s_add_u32 s14, s50, s80
	s_addc_u32 s15, s51, s81
	s_lshl_b32 s5, s12, 2
	s_add_i32 s5, s5, s34
	s_mul_hi_i32 s12, s4, s5
	s_mul_i32 s4, s4, s5
	s_add_u32 s4, s4, s10
	s_addc_u32 s5, s12, s11
	s_mul_i32 s10, s5, 0x180
	s_mul_hi_u32 s86, s4, 0x180
	s_add_i32 s86, s86, s10
	s_mul_i32 s87, s4, 0x180
	s_add_u32 s10, s14, s87
	s_addc_u32 s11, s15, s86
	s_lshl_b64 s[82:83], s[4:5], 8
	v_ashrrev_i32_e32 v36, 4, v162
	s_add_u32 s4, s8, s82
	v_lshlrev_b32_e32 v40, 3, v199
	v_ashrrev_i32_e32 v41, 3, v162
	s_movk_i32 s8, 0xc0
	v_ashrrev_i32_e32 v37, 31, v36
	s_addc_u32 s5, s13, s83
	v_and_b32_e32 v18, 0x78, v40
	v_add_u32_e32 v38, 32, v36
	v_and_b32_e32 v42, 7, v199
	v_mul_lo_u32 v16, v41, s8
	v_lshlrev_b64 v[48:49], 8, v[36:37]
	v_lshl_or_b32 v24, v42, 3, v16
	v_lshl_add_u64 v[16:17], s[4:5], 0, v[48:49]
	v_lshlrev_b32_e32 v18, 1, v18
	v_mov_b32_e32 v19, v161
	v_ashrrev_i32_e32 v39, 31, v38
	v_lshl_add_u64 v[52:53], v[16:17], 0, v[18:19]
	v_lshlrev_b64 v[16:17], 8, v[38:39]
	v_ashrrev_i32_e32 v25, 31, v24
	v_lshl_add_u64 v[16:17], s[4:5], 0, v[16:17]
	v_lshlrev_b64 v[50:51], 1, v[24:25]
	v_lshl_add_u64 v[20:21], v[16:17], 0, v[18:19]
	v_lshl_add_u64 v[54:55], s[10:11], 0, v[50:51]
	global_load_dwordx4 v[16:19], v[52:53], off
	s_nop 0
	global_load_dwordx4 v[20:23], v[20:21], off
	s_nop 0
	global_load_dwordx4 v[24:27], v[54:55], off
	global_load_dwordx4 v[28:31], v[54:55], off offset:128
	global_load_dwordx4 v[32:35], v[54:55], off offset:256
	s_mov_b64 s[4:5], 0x6000
	v_lshl_add_u64 v[68:69], v[54:55], 0, s[4:5]
	v_lshl_add_u64 v[56:57], v[52:53], 0, s[4:5]
	s_mov_b64 s[4:5], 0x4000
	v_lshl_add_u64 v[54:55], v[52:53], 0, s[4:5]
	global_load_dwordx4 v[52:55], v[54:55], off
	global_load_dwordx4 v[56:59], v[56:57], off
	global_load_dwordx4 v[60:63], v[68:69], off
	global_load_dwordx4 v[64:67], v[68:69], off offset:128
	global_load_dwordx4 v[68:71], v[68:69], off offset:256
	s_waitcnt vmcnt(13)
	ds_write_b128 v139, v[4:7] offset:4096
	s_waitcnt vmcnt(12)
	ds_write_b128 v139, v[12:15] offset:5120
	s_waitcnt vmcnt(11)
	ds_write_b128 v139, v[0:3] offset:6144
	s_waitcnt vmcnt(10)
	ds_write_b128 v139, v[8:11] offset:7168
	s_movk_i32 s4, 0x180
	v_and_b32_e32 v1, 0xfffff0, v36
	v_lshlrev_b32_e32 v2, 1, v36
	v_lshrrev_b32_e32 v3, 1, v36
	v_and_b32_e32 v5, 3, v36
	v_and_b32_e32 v0, 0x70, v162
	v_mul_lo_u32 v7, v41, s4
	v_lshlrev_b32_e32 v9, 4, v42
	v_and_or_b32 v1, v2, 8, v1
	v_and_or_b32 v2, v3, 4, v5
	v_and_b32_e32 v3, 0xfffff0, v38
	v_lshlrev_b32_e32 v5, 1, v38
	v_bfe_u32 v4, v40, 5, 2
	v_bitop3_b32 v0, v9, v7, v0 bitop3:0xde
	v_lshrrev_b32_e32 v1, 1, v1
	v_and_or_b32 v3, v5, 8, v3
	v_lshlrev_b32_e32 v173, 4, v199
	v_add_u32_e32 v159, 0, v0
	v_or_b32_e32 v0, v1, v4
	v_lshrrev_b32_e32 v1, 1, v3
	v_lshlrev_b32_e32 v8, 3, v170
	v_mad_u32_u24 v80, v170, s4, 0
	v_and_b32_e32 v6, 48, v173
	s_movk_i32 s4, 0x70
	v_lshlrev_b32_e32 v2, 6, v2
	v_lshlrev_b32_e32 v0, 9, v0
	v_or_b32_e32 v1, v1, v4
	v_bitop3_b32 v155, v160, v8, s4 bitop3:0x78
	v_or3_b32 v0, v0, v2, v6
	v_lshlrev_b32_e32 v1, 9, v1
	v_add_u32_e32 v156, v80, v155
	v_or3_b32 v1, v1, v2, v6
	v_add_u32_e32 v163, 0, v0
	v_add_u32_e32 v164, 0, v1
	s_waitcnt vmcnt(5)
	v_and_b32_e32 v76, 0x70, v8
	v_bitop3_b32 v175, v160, v76, 32 bitop3:0x36
	v_add_u32_e32 v169, v80, v175
	v_bitop3_b32 v176, v160, v76, 64 bitop3:0x36
	v_add_u32_e32 v168, v80, v176
	s_movk_i32 s4, 0x60
	v_bitop3_b32 v177, v160, v76, s4 bitop3:0x36
	v_add_u32_e32 v167, v80, v177
	s_movk_i32 s4, 0x80
	v_bitop3_b32 v178, v160, v76, s4 bitop3:0x36
	v_add_u32_e32 v165, v80, v178
	s_movk_i32 s4, 0xa0
	v_bitop3_b32 v181, v160, v76, s4 bitop3:0x36
	v_add_u32_e32 v166, v80, v181
	v_bitop3_b32 v182, v160, v76, s8 bitop3:0x36
	v_add_u32_e32 v158, v80, v182
	s_movk_i32 s4, 0xe0
	v_bitop3_b32 v183, v160, v76, s4 bitop3:0x36
	v_add_u32_e32 v157, v80, v183
	ds_write_b128 v163, v[16:19]
	ds_write_b128 v164, v[20:23]
	ds_write_b128 v159, v[24:27] offset:32768
	ds_write_b128 v159, v[28:31] offset:32896
	ds_write_b128 v159, v[32:35] offset:33024
	s_waitcnt lgkmcnt(0)
	s_barrier
	ds_read_b128 v[0:3], v156 offset:32768
	ds_read_b128 v[4:7], v156 offset:45056
	s_waitcnt lgkmcnt(1)
	v_mfma_f32_32x32x16_bf16 v[16:31], v[0:3], v[108:111], 0
	v_bitop3_b32 v184, v160, v76, s44 bitop3:0x36
	v_add_u32_e32 v154, v80, v184
	s_movk_i32 s4, 0x120
	v_bitop3_b32 v185, v160, v76, s4 bitop3:0x36
	s_waitcnt lgkmcnt(0)
	v_mfma_f32_32x32x16_bf16 v[32:47], v[4:7], v[108:111], 0
	ds_read_b128 v[0:3], v169 offset:32768
	ds_read_b128 v[4:7], v169 offset:45056
	v_add_u32_e32 v153, v80, v185
	s_waitcnt lgkmcnt(1)
	v_mfma_f32_32x32x16_bf16 v[16:31], v[0:3], v[104:107], v[16:31]
	s_movk_i32 s4, 0x140
	s_nop 0
	s_waitcnt lgkmcnt(0)
	v_mfma_f32_32x32x16_bf16 v[32:47], v[4:7], v[104:107], v[32:47]
	ds_read_b128 v[0:3], v168 offset:32768
	ds_read_b128 v[4:7], v168 offset:45056
	v_bitop3_b32 v186, v160, v76, s4 bitop3:0x36
	v_add_u32_e32 v180, v80, v186
	s_movk_i32 s4, 0x160
	v_bitop3_b32 v187, v160, v76, s4 bitop3:0x36
	v_add_u32_e32 v179, v80, v187
	s_mov_b32 s8, s9
	s_waitcnt lgkmcnt(1)
	v_mfma_f32_32x32x16_bf16 v[16:31], v[0:3], v[100:103], v[16:31]
	s_mov_b32 s10, s9
	s_mov_b32 s11, s9
	s_mov_b32 s12, s9
	s_mov_b32 s13, s9
	s_mov_b32 s14, s9
	s_mov_b32 s15, s9
	s_mov_b32 s16, s9
	s_waitcnt lgkmcnt(0)
	v_mfma_f32_32x32x16_bf16 v[32:47], v[4:7], v[100:103], v[32:47]
	ds_read_b128 v[0:3], v167 offset:32768
	ds_read_b128 v[4:7], v167 offset:45056
	s_mov_b32 s17, s9
	s_mov_b32 s18, s9
	s_mov_b32 s19, s9
	s_mov_b32 s20, s9
	s_mov_b32 s21, s9
	s_mov_b32 s22, s9
	s_waitcnt lgkmcnt(1)
	v_mfma_f32_32x32x16_bf16 v[16:31], v[0:3], v[96:99], v[16:31]
	s_mov_b32 s23, s9
	s_movk_i32 s68, 0xc0
	s_mov_b32 s85, 2
	v_add_u32_e32 v190, 0xe000, v80
	v_cmp_gt_u32_e64 s[4:5], 32, v141
	v_mov_b32_e32 v151, 0
	s_waitcnt lgkmcnt(0)
	v_mfma_f32_32x32x16_bf16 v[32:47], v[4:7], v[96:99], v[32:47]
	ds_read_b128 v[0:3], v165 offset:32768
	ds_read_b128 v[4:7], v139
	ds_read_b128 v[8:11], v165 offset:45056
	ds_read_b128 v[12:15], v139 offset:1024
	s_waitcnt lgkmcnt(2)
	v_mfma_f32_32x32x16_bf16 v[16:31], v[0:3], v[4:7], v[16:31]
	s_waitcnt lgkmcnt(1)
	v_mfma_f32_32x32x16_bf16 v[32:47], v[8:11], v[4:7], v[32:47]
	ds_read_b128 v[0:3], v166 offset:32768
	ds_read_b128 v[4:7], v166 offset:45056
	s_waitcnt lgkmcnt(1)
	v_mfma_f32_32x32x16_bf16 v[16:31], v[0:3], v[12:15], v[16:31]
	s_waitcnt lgkmcnt(0)
	v_mfma_f32_32x32x16_bf16 v[32:47], v[4:7], v[12:15], v[32:47]
	ds_read_b128 v[0:3], v158 offset:32768
	ds_read_b128 v[4:7], v139 offset:2048
	ds_read_b128 v[8:11], v158 offset:45056
	ds_read_b128 v[12:15], v139 offset:3072
	s_waitcnt lgkmcnt(2)
	v_mfma_f32_32x32x16_bf16 v[16:31], v[0:3], v[4:7], v[16:31]
	ds_read_b128 v[0:3], v157 offset:32768
	s_waitcnt lgkmcnt(2)
	v_mfma_f32_32x32x16_bf16 v[32:47], v[8:11], v[4:7], v[32:47]
	ds_read_b128 v[4:7], v157 offset:45056
	s_waitcnt lgkmcnt(1)
	v_mfma_f32_32x32x16_bf16 v[16:31], v[0:3], v[12:15], v[16:31]
	ds_read_b128 v[0:3], v154 offset:32768
	s_waitcnt lgkmcnt(1)
	v_mfma_f32_32x32x16_bf16 v[32:47], v[4:7], v[12:15], v[32:47]
	ds_read_b128 v[4:7], v139 offset:4096
	ds_read_b128 v[8:11], v154 offset:45056
	ds_read_b128 v[12:15], v139 offset:5120
	s_waitcnt lgkmcnt(2)
	v_mfma_f32_32x32x16_bf16 v[16:31], v[0:3], v[4:7], v[16:31]
	ds_read_b128 v[0:3], v153 offset:32768
	s_nop 0
	s_nop 0
	s_nop 0
	s_waitcnt lgkmcnt(2)
	v_mfma_f32_32x32x16_bf16 v[32:47], v[8:11], v[4:7], v[32:47]
	ds_read_b128 v[4:7], v153 offset:45056
	v_and_b32_e32 v8, 0x3fffffc0, v162
	v_lshlrev_b32_e32 v9, 3, v141
	v_lshl_add_u32 v137, v8, 2, s0
	v_lshl_add_u32 v174, v170, 2, v137
	s_waitcnt lgkmcnt(1)
	v_mfma_f32_32x32x16_bf16 v[16:31], v[0:3], v[12:15], v[16:31]
	v_and_b32_e32 v0, 0xc0, v140
	v_and_or_b32 v8, v9, 24, v0
	ds_read_b128 v[0:3], v180 offset:32768
	v_and_b32_e32 v9, 0x100, v9
	s_waitcnt lgkmcnt(1)
	v_mfma_f32_32x32x16_bf16 v[32:47], v[4:7], v[12:15], v[32:47]
	v_lshlrev_b32_e32 v4, 1, v141
	v_and_b32_e32 v10, 32, v4
	ds_read_b128 v[4:7], v139 offset:6144
	v_or3_b32 v81, v8, v10, v9
	ds_read_b128 v[8:11], v180 offset:45056
	ds_read_b128 v[72:75], v139 offset:7168
	ds_read_b128 v[76:79], v179 offset:45056
	v_add_u32_e32 v152, 0, v81
	s_waitcnt lgkmcnt(3)
	v_mfma_f32_32x32x16_bf16 v[16:31], v[0:3], v[4:7], v[16:31]
	ds_read_b128 v[0:3], v179 offset:32768
	s_waitcnt vmcnt(0)
	s_waitcnt vmcnt(4)
	ds_write_b128 v163, v[52:55] offset:16384
	s_waitcnt vmcnt(3)
	ds_write_b128 v164, v[56:59] offset:16384
	s_waitcnt vmcnt(2)
	ds_write_b128 v159, v[60:63] offset:57344
	s_waitcnt vmcnt(1)
	ds_write_b128 v159, v[64:67] offset:57472
	s_waitcnt vmcnt(0)
	ds_write_b128 v159, v[68:71] offset:57600
	s_waitcnt lgkmcnt(8)
	v_mfma_f32_32x32x16_bf16 v[32:47], v[8:11], v[4:7], v[32:47]
	s_waitcnt lgkmcnt(0)
	s_barrier
	v_mfma_f32_32x32x16_bf16 v[16:31], v[0:3], v[72:75], v[16:31]
	v_mov_b64_e32 v[0:1], s[8:9]
	v_mov_b64_e32 v[2:3], s[10:11]
	v_mov_b64_e32 v[4:5], s[12:13]
	v_mov_b64_e32 v[6:7], s[14:15]
	v_mov_b64_e32 v[8:9], s[16:17]
	v_mov_b64_e32 v[10:11], s[18:19]
	v_mov_b64_e32 v[12:13], s[20:21]
	v_mfma_f32_32x32x16_bf16 v[32:47], v[76:79], v[72:75], v[32:47]
	s_nop 3
	v_max_f32_e32 v72, v17, v17
	v_max_f32_e32 v73, v16, v16
	v_max_f32_e32 v72, v73, v72
	v_max3_f32 v72, v72, v18, v19
	v_max3_f32 v72, v72, v20, v21
	v_max3_f32 v72, v72, v22, v23
	v_max3_f32 v72, v72, v24, v25
	v_max3_f32 v72, v72, v26, v27
	v_max3_f32 v72, v72, v28, v29
	v_max3_f32 v72, v72, v30, v31
	v_max3_f32 v72, v72, v32, v33
	v_max3_f32 v72, v72, v34, v35
	v_max3_f32 v72, v72, v36, v37
	v_max3_f32 v72, v72, v38, v39
	v_max3_f32 v72, v72, v40, v41
	v_max3_f32 v72, v72, v42, v43
	v_max3_f32 v72, v72, v44, v45
	v_max3_f32 v72, v72, v46, v47
	v_mov_b32_e32 v73, v72
	s_nop 1
	v_permlane32_swap_b32_e32 v72, v73
	v_max_f32_e32 v73, v73, v73
	v_max_f32_e32 v72, v72, v72
	v_max_f32_e32 v72, v72, v73
	v_add_f32_e32 v73, 0x7149f2ca, v72
	v_cmp_ge_f32_e32 vcc, s1, v73
	s_cmp_eq_u64 vcc, exec
	v_max_f32_e32 v52, 0xf149f2ca, v72
	s_cselect_b64 vcc, -1, 0
	v_cndmask_b32_e32 v188, v52, v198, vcc
	v_sub_f32_e32 v53, 0xf149f2ca, v52
	v_mul_f32_e32 v52, 0xbdd53b94, v188
	v_fmamk_f32 v16, v16, 0x3dd53b94, v52
	v_exp_f32_e32 v133, v16
	v_fmamk_f32 v16, v17, 0x3dd53b94, v52
	v_exp_f32_e32 v214, v16
	v_fmamk_f32 v16, v18, 0x3dd53b94, v52
	v_exp_f32_e32 v134, v16
	v_fmamk_f32 v16, v19, 0x3dd53b94, v52
	v_exp_f32_e32 v215, v16
	v_fmamk_f32 v16, v20, 0x3dd53b94, v52
	v_exp_f32_e32 v213, v16
	v_fmamk_f32 v16, v21, 0x3dd53b94, v52
	v_exp_f32_e32 v216, v16
	v_fmamk_f32 v16, v22, 0x3dd53b94, v52
	v_exp_f32_e32 v135, v16
	v_fmamk_f32 v16, v23, 0x3dd53b94, v52
	v_exp_f32_e32 v212, v16
	v_fmamk_f32 v16, v24, 0x3dd53b94, v52
	v_mul_f32_e32 v53, 0x3dd53b94, v53
	v_exp_f32_e32 v146, v16
	v_fmamk_f32 v16, v25, 0x3dd53b94, v52
	v_exp_f32_e32 v53, v53
	v_exp_f32_e32 v148, v16
	v_fmamk_f32 v16, v26, 0x3dd53b94, v52
	v_mov_b64_e32 v[14:15], s[22:23]
	v_exp_f32_e32 v147, v16
	v_fmamk_f32 v16, v27, 0x3dd53b94, v52
	s_add_i32 s8, 0, 0x4000
	v_exp_f32_e32 v149, v16
	v_fmamk_f32 v16, v28, 0x3dd53b94, v52
	s_add_u32 s10, s80, s87
	v_exp_f32_e32 v128, v16
	v_fmamk_f32 v16, v29, 0x3dd53b94, v52
	s_addc_u32 s11, s81, s86
	v_pk_fma_f32 v[112:113], v[46:47], s[72:73], v[52:53] op_sel_hi:[1,0,0]
	v_pk_fma_f32 v[118:119], v[44:45], s[72:73], v[52:53] op_sel_hi:[1,0,0]
	v_pk_fma_f32 v[122:123], v[42:43], s[72:73], v[52:53] op_sel_hi:[1,0,0]
	v_pk_fma_f32 v[114:115], v[40:41], s[72:73], v[52:53] op_sel_hi:[1,0,0]
	v_pk_fma_f32 v[116:117], v[38:39], s[72:73], v[52:53] op_sel_hi:[1,0,0]
	v_pk_fma_f32 v[120:121], v[36:37], s[72:73], v[52:53] op_sel_hi:[1,0,0]
	v_pk_fma_f32 v[124:125], v[34:35], s[72:73], v[52:53] op_sel_hi:[1,0,0]
	v_pk_fma_f32 v[126:127], v[32:33], s[72:73], v[52:53] op_sel_hi:[1,0,0]
	v_exp_f32_e32 v130, v16
	v_fmamk_f32 v16, v30, 0x3dd53b94, v52
	v_fmac_f32_e32 v52, 0x3dd53b94, v31
	s_add_u32 s6, s6, s82
	v_exp_f32_e32 v129, v16
	v_exp_f32_e32 v131, v52
	s_addc_u32 s7, s7, s83
	v_and_b32_e32 v18, 15, v199
	v_lshl_add_u64 v[16:17], s[6:7], 0, v[48:49]
	v_lshlrev_b32_e32 v18, 4, v18
	v_mov_b32_e32 v19, v161
	v_cndmask_b32_e64 v189, v53, 1.0, vcc
	v_lshl_add_u64 v[142:143], s[10:11], 0, v[50:51]
	v_lshl_add_u64 v[144:145], v[16:17], 0, v[18:19]
	v_mov_b64_e32 v[62:63], v[14:15]
	v_mov_b64_e32 v[46:47], v[14:15]
	v_mov_b64_e32 v[30:31], v[14:15]
	v_add_u32_e32 v150, s8, v81
	v_mov_b64_e32 v[60:61], v[12:13]
	v_mov_b64_e32 v[58:59], v[10:11]
	v_mov_b64_e32 v[56:57], v[8:9]
	v_mov_b64_e32 v[54:55], v[6:7]
	v_mov_b64_e32 v[52:53], v[4:5]
	v_mov_b64_e32 v[50:51], v[2:3]
	v_mov_b64_e32 v[48:49], v[0:1]
	v_mov_b64_e32 v[44:45], v[12:13]
	v_mov_b64_e32 v[42:43], v[10:11]
	v_mov_b64_e32 v[40:41], v[8:9]
	v_mov_b64_e32 v[38:39], v[6:7]
	v_mov_b64_e32 v[36:37], v[4:5]
	v_mov_b64_e32 v[34:35], v[2:3]
	v_mov_b64_e32 v[32:33], v[0:1]
	v_mov_b64_e32 v[28:29], v[12:13]
	v_mov_b64_e32 v[26:27], v[10:11]
	v_mov_b64_e32 v[24:25], v[8:9]
	v_mov_b64_e32 v[22:23], v[6:7]
	v_mov_b64_e32 v[20:21], v[4:5]
	v_mov_b64_e32 v[18:19], v[2:3]
	v_mov_b64_e32 v[16:17], v[0:1]
	v_readlane_b32 s86, v254, 19
	v_readlane_b32 s87, v254, 20
